# previous best plus instruction prefetch: during each grid barrier waves 1-7 stream the next phase's code (PC-relative, 42 KB) into L2 through the data path
# speedup vs baseline: 1.0082x; 1.0082x over previous
; __device__ __forceinline__ void xcd_barrier(const XcdBarrier& b) {
;     asm volatile("s_waitcnt vmcnt(0)" ::: "memory");
;     __syncthreads();
;     if (threadIdx.x == 0) {
;         unsigned* bar = b.bar;
;         __builtin_amdgcn_s_waitcnt(0);
;         unsigned nloc = b.st[0], nx = b.st[1];
;         if (nloc == 0u) { xcd_barrier_complete(bar, b.x, nloc, nx); b.st[0] = nloc; b.st[1] = nx; }
;         const unsigned old = xb_add(&bar[XB_XSUB(b.x)], 1u);
;         const unsigned gen = old / nloc;
;         if (old + 1u == (gen + 1u) * nloc) {
;             __builtin_amdgcn_fence(__ATOMIC_RELEASE, "agent");
;             asm volatile("s_waitcnt vmcnt(0)" ::: "memory");
;             const unsigned og = xb_add(&bar[XB_TOP], 1u);
;             const unsigned tg = og / nx;
;             if (og + 1u == (tg + 1u) * nx) xb_add(&bar[XB_TOPGEN], 1u);
;             else XB_SPIN(xb_ld(&bar[XB_TOPGEN]) == tg, bar);
;             __builtin_amdgcn_fence(__ATOMIC_ACQUIRE, "agent");
;             xb_add(&bar[XB_XGEN(b.x)], 1u);
;             asm volatile("s_waitcnt vmcnt(0)" ::: "memory");
;         } else {
;             XB_SPIN(xb_ld(&bar[XB_XGEN(b.x)]) == gen, bar);
;             __builtin_amdgcn_fence(__ATOMIC_ACQUIRE, "agent");
;             asm volatile("s_waitcnt vmcnt(0)" ::: "memory");
;         }
;     }
;     __syncthreads();
; }
; template <int PART> __device__ __forceinline__ void phase0(const Params& p, LAS unsigned char* lds) {
;     constexpr int SKIP = PART == 0 ? 0 : PART == 1 ? 48 : 192;
;     const int tid = threadIdx.x, lane = tid & 63, wave = tid >> 6;
;     const int gw = ((int)blockIdx.x - SKIP) * NWAVES + wave, NGW = ((int)gridDim.x - SKIP) * NWAVES;
;     if (gw < 0) return;
;     const int gt = blockIdx.x * NTHREADS + tid, NGT = gridDim.x * NTHREADS;
;     unsigned char* ws = p.ws;
;     LAS float* scr = (LAS float*)(lds + wave * 16640);
;     constexpr int I0 = 32 * 192, I1 = 32 * 112, I2 = 32 * 192, I3 = 96 * 32, I4 = 32 * 32, I5 = 32 * 32, I6 = 16 * 32, I7 = 64, I8 = 128, I9 = 128;
;     constexpr int NIT = I0 + I1 + I2 + I3 + I4 + I5 + I6 + I7 + I8 + I9;
;     constexpr int U0 = I0 + I1, U1 = U0 + I2 / 2, D0 = I0 + I1 + I2, D1 = D0 + I3;
;     constexpr int CUT = (U1 - U0) + I3;
;     constexpr int LO = PART == 0 ? 0 : PART == 1 ? I0 : PART == 2 ? U0 : D0, HI = PART == 0 ? I0 : PART == 1 ? NIT - CUT : PART == 2 ? U1 : D1;
.LBB0_88:
	s_or_b64 exec, exec, s[4:5]
	v_readfirstlane_b32 s98, v212
	s_lshr_b32 s98, s98, 6
	s_cmp_eq_u32 s98, 0
	s_cbranch_scc1 .Lipf_skip_0
	s_getpc_b64 s[100:101]
	v_mbcnt_lo_u32_b32 v0, -1, 0
	v_mbcnt_hi_u32_b32 v0, -1, v0
	v_lshlrev_b32_e32 v0, 4, v0
	s_lshl_b32 s98, s98, 10
	v_add_u32_e32 v0, s98, v0
	global_load_dwordx4 v[2:5], v0, s[100:101]
	s_add_u32 s100, s100, 0x1c00
	s_addc_u32 s101, s101, 0
	global_load_dwordx4 v[2:5], v0, s[100:101]
	s_add_u32 s100, s100, 0x1c00
	s_addc_u32 s101, s101, 0
	global_load_dwordx4 v[2:5], v0, s[100:101]
	s_add_u32 s100, s100, 0x1c00
	s_addc_u32 s101, s101, 0
	global_load_dwordx4 v[2:5], v0, s[100:101]
	s_add_u32 s100, s100, 0x1c00
	s_addc_u32 s101, s101, 0
	global_load_dwordx4 v[2:5], v0, s[100:101]
	s_add_u32 s100, s100, 0x1c00
	s_addc_u32 s101, s101, 0
	global_load_dwordx4 v[2:5], v0, s[100:101]
	s_waitcnt vmcnt(0)
.Lipf_skip_0:
	s_cmp_gt_i32 s2, 47
	s_waitcnt lgkmcnt(0)
	s_barrier
	s_cbranch_scc0 .LBB0_124
	v_add_u32_e32 v0, 0xfffffe80, v210
	s_movk_i32 s0, 0x2540
	v_cmp_gt_u32_e32 vcc, s0, v0
	s_and_saveexec_b64 s[4:5], vcc
	s_cbranch_execz .LBB0_125
	v_readlane_b32 s0, v255, 6
	v_lshlrev_b32_e32 v0, 3, v212
	v_readlane_b32 s1, v255, 7
	v_and_b32_e32 v32, 56, v0
	s_movk_i32 s1, 0x4100
	v_mov_b32_e32 v1, 0
	v_lshrrev_b32_e32 v44, 3, v184
	v_lshlrev_b32_e32 v0, 1, v32
	v_mad_u32_u24 v4, v213, s1, 0
	v_lshlrev_b32_e32 v30, 2, v184
	v_mul_u32_u24_e32 v5, 0x104, v32
	v_lshl_add_u64 v[16:17], s[84:85], 0, v[0:1]
	v_lshlrev_b32_e32 v0, 2, v44
	s_mov_b64 s[8:9], 0x5900000
	v_add_u32_e32 v43, v4, v30
	v_add3_u32 v45, v4, v5, v0
	v_lshl_add_u64 v[4:5], v[16:17], 0, s[8:9]
	s_mov_b64 s[8:9], 0x5d00000
	v_lshl_add_u64 v[6:7], v[16:17], 0, s[8:9]
	s_mov_b64 s[8:9], 0x6500000
	v_lshl_add_u64 v[8:9], v[16:17], 0, s[8:9]
	s_mov_b64 s[8:9], 0xe00000
	v_lshl_add_u64 v[10:11], v[16:17], 0, s[8:9]
	s_mov_b64 s[8:9], 0x2600000
	v_lshl_add_u64 v[12:13], v[16:17], 0, s[8:9]
	s_mov_b64 s[8:9], 0x9d00000
	s_mov_b64 s[6:7], 0x5680000
	v_lshl_add_u64 v[14:15], v[16:17], 0, s[8:9]
	s_mov_b64 s[8:9], 0x6d00000
	s_addk_i32 s0, 0xfe80
	v_lshl_add_u64 v[2:3], v[16:17], 0, s[6:7]
	v_lshl_add_u64 v[16:17], v[16:17], 0, s[8:9]
	v_readlane_b32 s8, v254, 33
	v_readlane_b32 s52, v254, 17
	s_add_u32 s6, s84, 0x5600000
	v_mov_b32_e32 v31, v1
	v_readlane_b32 s9, v254, 34
	v_readlane_b32 s10, v254, 35
	v_readlane_b32 s11, v254, 36
	v_readlane_b32 s12, v254, 37
	v_readlane_b32 s13, v254, 38
	v_readlane_b32 s14, v254, 39
	v_readlane_b32 s15, v254, 40
	v_readlane_b32 s20, v254, 45
	v_readlane_b32 s21, v254, 46
	v_readlane_b32 s22, v254, 47
	v_readlane_b32 s23, v254, 48
	v_readlane_b32 s53, v254, 18
	v_readlane_b32 s54, v254, 19
	v_readlane_b32 s55, v254, 20
	v_readlane_b32 s56, v254, 21
	v_readlane_b32 s57, v254, 22
	v_readlane_b32 s58, v254, 23
	v_readlane_b32 s59, v254, 24
	v_readlane_b32 s60, v254, 25
	v_readlane_b32 s61, v254, 26
	v_readlane_b32 s62, v254, 27
	v_readlane_b32 s63, v254, 28
	v_readlane_b32 s64, v254, 29
	v_readlane_b32 s65, v254, 30
	v_add_u32_e32 v42, 0x1680, v210
	v_or_b32_e32 v46, 8, v44
	v_or_b32_e32 v47, 16, v44
	v_or_b32_e32 v48, 24, v44
	v_or_b32_e32 v49, 32, v44
	v_or_b32_e32 v50, 40, v44
	v_or_b32_e32 v51, 48, v44
	v_or_b32_e32 v52, 56, v44
	s_addc_u32 s7, s85, 0
	v_lshl_add_u64 v[18:19], s[8:9], 0, v[30:31]
	v_lshl_add_u64 v[20:21], s[10:11], 0, v[30:31]
	v_lshl_add_u64 v[22:23], s[12:13], 0, v[30:31]
	v_lshl_add_u64 v[24:25], s[20:21], 0, v[30:31]
	v_lshl_add_u64 v[26:27], s[14:15], 0, v[30:31]
	v_lshl_add_u64 v[28:29], s[64:65], 0, v[30:31]
	v_lshl_add_u64 v[30:31], s[52:53], 0, v[30:31]
	s_movk_i32 s1, 0x25ff
	s_movk_i32 s3, 0x3dff
	s_movk_i32 s35, 0x1000
	s_movk_i32 s52, 0x2000
	s_movk_i32 s53, 0x3000
	s_movk_i32 s54, 0x4000
	s_movk_i32 s55, 0x5000
	s_movk_i32 s56, 0x6000
	s_movk_i32 s57, 0x7000
	s_mov_b32 s58, 0x8000
	s_mov_b32 s59, 0x9000
	s_mov_b32 s60, 0xa000
	s_mov_b32 s61, 0xb000
	s_mov_b32 s62, 0xc000
	s_mov_b32 s63, 0xd000
	s_mov_b32 s22, 0xe000
	s_mov_b32 s23, 0xf000
	v_lshlrev_b32_e32 v32, 1, v32
	s_mov_b32 s24, 0x54000
	s_mov_b32 s25, 0xa8000
	s_mov_b32 s82, 0xfc000
	s_mov_b32 s83, 0x150000
	v_mov_b32_e32 v53, 0x80
	v_mov_b32_e32 v54, 0xffffabc0
	v_mov_b32_e32 v55, 0xffffab40
	v_lshlrev_b32_e32 v34, 2, v184
	v_mov_b32_e32 v56, 6
	s_mov_b32 s88, 0x1a4000
	s_mov_b64 s[8:9], 0
	v_readlane_b32 s16, v254, 41
	v_readlane_b32 s17, v254, 42
	v_readlane_b32 s18, v254, 43
	v_readlane_b32 s19, v254, 44
	v_readlane_b32 s66, v254, 31
	v_readlane_b32 s67, v254, 32
	s_branch .LBB0_92

;     __device__ __forceinline__ bool next(int i, Unit& u) const {
;         const long L = (long)i * G + c; const int nwg = nM * nN; if (L >= nwg) return false;
;         int wgid = (int)L; { const int q = nwg / 8, r = nwg % 8, xcd = wgid % 8, off = wgid / 8; wgid = (xcd < r ? xcd * (q + 1) : r * (q + 1) + (xcd - r) * q) + off; }
;         const int nig = 8 * nN, gid = wgid / nig, fm = gid * 8, gsz = (nM - fm) < 8 ? (nM - fm) : 8;
;         u.pm = fm + ((wgid % nig) % gsz); u.pn = (wgid % nig) / gsz; u.tag = 0;
;         u.A = A + (size_t)u.pm * a_tile + (size_t)((u.pn >> a_sh) * a_mul); u.B = B + (size_t)u.pn * b_tile; u.nt = nt; return true;
; __global__ void __launch_bounds__(NTHREADS, 2) fwd_megakernel(Params p) {
;     ...
;     if (PHASE_MASK & 8u) {
;         Sched S{(const char*)(ws + WS_H), (const char*)(ws + WS_WIN), TA * DM, TA * DM, MTOK / 256, INW / 256, DM / 64, G, c, 0, 0};
;         EpiBf16 E{(bf16_t*)(ws + WS_Z), INW, 12};
;         gemm_phase(lds, DM, DM, S, E);
.Lipf_skip_1:
	s_add_u32 s3, s84, 0xb900000
	s_addc_u32 s16, s85, 0
	s_add_u32 s36, s84, 0x9d00000
	s_addc_u32 s37, s85, 0
	v_mov_b32_e32 v8, v212
	s_cmpk_lt_i32 s2, 0x3f0
	s_waitcnt lgkmcnt(0)
	s_barrier
	s_cselect_b64 s[0:1], -1, 0
	s_cmpk_gt_i32 s2, 0x3ef
	v_readfirstlane_b32 s17, v8
	s_cbranch_scc1 .LBB0_228
	s_ashr_i32 s4, s2, 31
	s_lshr_b32 s4, s4, 29
	s_add_i32 s4, s2, s4
	s_ashr_i32 s5, s4, 3
	s_and_b32 s4, s4, -8
	s_sub_i32 s4, s2, s4
	s_cmp_lt_i32 s4, 0
	s_movk_i32 s6, 0x7f
	s_cselect_b32 s6, s6, 0x7e
	s_mul_i32 s4, s4, s6
	s_add_i32 s4, s4, s5
	s_mul_hi_i32 s5, s4, 0x92492493
	s_add_i32 s5, s5, s4
	s_lshr_b32 s6, s5, 31
	s_ashr_i32 s5, s5, 7
	s_add_i32 s5, s5, s6
	s_lshl_b32 s6, s5, 3
	s_sub_i32 s7, 36, s6
	s_mulk_i32 s5, 0xe0
	s_min_u32 s7, s7, 8
	s_sub_i32 s8, s4, s5
	s_sext_i32_i16 s4, s8
	v_cvt_f32_ubyte0_e32 v1, s7
	v_cvt_f32_i32_e32 v0, s4
	v_rcp_iflag_f32_e32 v2, v1
	s_ashr_i32 s4, s4, 30
	s_or_b32 s9, s4, 1
	v_mul_f32_e32 v2, v0, v2
	v_trunc_f32_e32 v2, v2
	v_fma_f32 v0, -v2, v1, v0
	v_cvt_i32_f32_e32 v2, v2
	v_cmp_ge_f32_e64 s[4:5], |v0|, v1
	s_and_b64 s[4:5], s[4:5], exec
	s_cselect_b32 s4, s9, 0
	v_readfirstlane_b32 s5, v2
	s_add_i32 s4, s5, s4
	s_mul_i32 s5, s4, s7
	s_sub_i32 s5, s8, s5
	s_sext_i32_i16 s5, s5
	s_add_i32 s6, s6, s5
	s_ashr_i32 s7, s6, 31
	s_lshl_b64 s[8:9], s[6:7], 20
	s_add_u32 s54, s3, s8
	s_sext_i32_i16 s78, s4
	s_addc_u32 s55, s16, s9
	s_bfe_i64 s[4:5], s[4:5], 0x100000
	s_lshl_b64 s[4:5], s[4:5], 20
	s_add_u32 s56, s36, s4
	s_addc_u32 s57, s37, s5
	s_add_u32 s40, s84, 0xdd00000
	s_addc_u32 s41, s85, 0
	s_andn2_b64 vcc, exec, s[0:1]
	s_cbranch_vccz .LBB0_229
	s_branch .LBB0_272

; __device__ __forceinline__ void phase_mixprep(const Params& p) {
;     const int gt = blockIdx.x * NTHREADS + threadIdx.x, NGT = gridDim.x * NTHREADS;
;     const bf16_t* Z = (const bf16_t*)(p.ws + WS_Z); bf16_t* Dp = (bf16_t*)(p.ws + WS_DP); bf16_t* XC = (bf16_t*)(p.ws + WS_XC);
;     for (int it = gt; it < (MPROMPT / 16) * 256; it += NGT) {
;         const int c4 = it & 255, run = it >> 8, ch0 = 4 * c4, g = ch0 >> 8, r0 = run * 16, t0 = r0 & (SEQ - 1);
;         const bf16_t* zp = Z + (size_t)r0 * INW + ch0;
;         switch (g) { case 0: pool_run<2>(zp, Dp + (size_t)r0 * PW + ch0, t0); break; case 1: pool_run<4>(zp, Dp + (size_t)r0 * PW + ch0, t0); break;
;                      case 2: pool_run<8>(zp, Dp + (size_t)r0 * PW + ch0, t0); break; default: pool_run<16>(zp, Dp + (size_t)r0 * PW + ch0, t0); break; }
.Lipf_skip_2:
	s_lshl_b32 s3, s86, 9
	v_lshl_add_u32 v220, s2, 9, v212
	s_add_u32 s54, s84, 0x15b00000
	s_mov_b32 s0, 0x20000
	s_addc_u32 s55, s85, 0
	v_cmp_gt_i32_e32 vcc, s0, v220
	s_waitcnt lgkmcnt(0)
	s_barrier
	s_and_saveexec_b64 s[6:7], vcc
	s_cbranch_execz .LBB0_437
	v_lshlrev_b32_e32 v0, 2, v212
	v_lshl_add_u32 v66, s2, 11, v0
	s_lshl_b32 s14, s86, 11
	s_mov_b64 s[8:9], 0
	s_movk_i32 s15, 0x3800
	v_mov_b64_e32 v[0:1], s[40:41]
	v_mov_b32_e32 v3, 0
	s_movk_i32 s16, 0x3000
	s_movk_i32 s17, 0x7000
	s_movk_i32 s18, 0x1000
	s_movk_i32 s19, 0x2000
	s_movk_i32 s20, 0x4000
	s_movk_i32 s21, 0x5000
	s_movk_i32 s35, 0x6000
	s_mov_b32 s52, 0x3d800000
	s_mov_b32 s53, 0x3e000000
	s_mov_b32 s56, 0x3e800000
	s_mov_b32 s57, 0x1ffff
	v_mov_b32_e32 v67, v220
	s_branch .LBB0_329

; #define LAS __attribute__((address_space(3)))
; #define PG8_WAIT_V(n) asm volatile("s_waitcnt vmcnt(" #n ")" ::: "memory")
; #define PG8_BAR __builtin_amdgcn_s_barrier()
; template <class Epi, class S_t>
; __device__ __forceinline__ void gemm_phase(LAS unsigned char* lds, int lda, int ldb, const S_t& S, const Epi& E) {
;     int tid = threadIdx.x; asm volatile("" : "+v"(tid));
;     const int wid = __builtin_amdgcn_readfirstlane(tid >> 6), lane = tid & 63, wr = wid >> 2, wc = wid & 3, fr = lane & 15, fq = lane >> 4;
;     unsigned voffA[2], voffB[2];
; #pragma unroll
;     for (int i = 0; i < 2; ++i) { int R, C; stage_rc(tid * 16 + i * 8192, R, C); const int Rb = Epi::PERM ? ((R & ~31) + perm32(R & 31)) : R;
;         voffA[i] = (unsigned)(R * lda + C) * 2u; voffB[i] = (unsigned)(Rb * ldb + C) * 2u; }
;     const size_t kstep = (size_t)(BK * 2);
;     const size_t hstepA = (size_t)HALF * lda * 2, hstepB = (size_t)HALF * ldb * 2;
;     const unsigned ldsw = (unsigned)wid * 1024u;
;     const int aoff = lds_byte(wr * 64 + fr, fq * 8), boff = lds_byte(wc * 32 + fr, fq * 8);
;     ...
;     Unit cur, nxt; int ui = 0;
;     if (!S.next(0, cur)) return;
;     f32x4 acc[2][2][4][2];
; #pragma unroll
;     for (int a = 0; a < 2; ++a)
; #pragma unroll
;         for (int b = 0; b < 2; ++b)
; #pragma unroll
;             for (int m = 0; m < 4; ++m)
; #pragma unroll
;                 for (int n = 0; n < 2; ++n) acc[a][b][m][n] = (f32x4){0.f, 0.f, 0.f, 0.f};
;     bf16x8 At[4][2], B0[2][2], B1[2][2];
;     const char* cA = cur.A; const char* cB = cur.B;
;     PG8_STAGE(PG8_SB(0, 0), cB, voffB); PG8_STAGE(PG8_SA(0, 0), cA, voffA); PG8_STAGE(PG8_SB(0, 1), cB + hstepB, voffB); PG8_STAGE(PG8_SA(0, 1), cA + hstepA, voffA);
;     if (wr == 1) PG8_BAR;
;     PG8_WAIT_V(4); PG8_BAR;
;     PG8_STAGE(PG8_SB(1, 0), cB + kstep, voffB); PG8_STAGE(PG8_SA(1, 0), cA + kstep, voffA); PG8_STAGE(PG8_SB(1, 1), cB + hstepB + kstep, voffB);
;     PG8_WAIT_V(6); PG8_BAR;
; __global__ void __launch_bounds__(NTHREADS, 2) fwd_megakernel(Params p) {
;     ...
;         { Sched S{(const char*)(ws + WS_DP), (const char*)(ws + WS_WGRP), TA * PW, TA * 256, MTOK / 256, 4, 4, G, c, 0, 512};
;           EpiPool E{(bf16_t*)(ws + WS_YP), p.in[I_PSCALE]};
;           gemm_phase(lds, PW, 256, S, E); }
.LBB0_528:
	s_or_b64 exec, exec, s[6:7]
	v_readfirstlane_b32 s98, v212
	s_lshr_b32 s98, s98, 6
	s_cmp_eq_u32 s98, 0
	s_cbranch_scc1 .Lipf_skip_3
	s_getpc_b64 s[100:101]
	v_mbcnt_lo_u32_b32 v0, -1, 0
	v_mbcnt_hi_u32_b32 v0, -1, v0
	v_lshlrev_b32_e32 v0, 4, v0
	s_lshl_b32 s98, s98, 10
	v_add_u32_e32 v0, s98, v0
	global_load_dwordx4 v[2:5], v0, s[100:101]
	s_add_u32 s100, s100, 0x1c00
	s_addc_u32 s101, s101, 0
	global_load_dwordx4 v[2:5], v0, s[100:101]
	s_add_u32 s100, s100, 0x1c00
	s_addc_u32 s101, s101, 0
	global_load_dwordx4 v[2:5], v0, s[100:101]
	s_add_u32 s100, s100, 0x1c00
	s_addc_u32 s101, s101, 0
	global_load_dwordx4 v[2:5], v0, s[100:101]
	s_add_u32 s100, s100, 0x1c00
	s_addc_u32 s101, s101, 0
	global_load_dwordx4 v[2:5], v0, s[100:101]
	s_add_u32 s100, s100, 0x1c00
	s_addc_u32 s101, s101, 0
	global_load_dwordx4 v[2:5], v0, s[100:101]
	s_waitcnt vmcnt(0)
.Lipf_skip_3:
	s_add_u32 s46, s84, 0x19100000
	v_writelane_b32 v255, s36, 12
	s_addc_u32 s47, s85, 0
	v_mov_b32_e32 v8, v212
	v_writelane_b32 v255, s37, 13
	s_waitcnt lgkmcnt(0)
	s_barrier
	s_cmpk_gt_i32 s2, 0x8f
	v_readfirstlane_b32 s4, v8
	s_cbranch_scc1 .LBB0_540
	v_lshlrev_b32_e32 v0, 4, v8
	v_add_u32_e32 v1, 0x2000, v0
	v_ashrrev_i32_e32 v2, 31, v1
	v_lshrrev_b32_e32 v2, 22, v2
	v_add_u32_e32 v2, v1, v2
	v_ashrrev_i32_e32 v2, 10, v2
	v_mul_i32_i24_e32 v3, 0x400, v2
	v_sub_u32_e32 v1, v1, v3
	v_lshrrev_b32_e32 v3, 4, v1
	v_bitop3_b32 v1, v3, v1, 32 bitop3:0x6c
	v_ashrrev_i32_e32 v3, 31, v1
	v_lshrrev_b32_e32 v3, 26, v3
	v_add_u32_e32 v3, v1, v3
	v_lshlrev_b32_e32 v5, 3, v2
	v_ashrrev_i32_e32 v4, 6, v3
	v_and_b32_e32 v5, -16, v5
	v_and_b32_e32 v3, 0xc0, v3
	v_add_u32_e32 v5, v4, v5
	v_sub_u32_e32 v1, v1, v3
	v_mov_b32_e32 v3, 1
	v_and_b32_e32 v4, 3, v4
	s_mov_b32 s6, 0x7fffe0
	v_lshrrev_b32_e32 v6, 2, v5
	v_lshlrev_b32_e32 v7, 1, v5
	v_lshlrev_b32_e32 v2, 5, v2
	v_ashrrev_i16_sdwa v1, v3, sext(v1) dst_sel:DWORD dst_unused:UNUSED_PAD src0_sel:DWORD src1_sel:BYTE_0
	v_and_or_b32 v4, v5, s6, v4
	v_and_b32_e32 v6, 4, v6
	v_and_b32_e32 v7, 24, v7
	v_and_b32_e32 v2, 32, v2
	v_bfe_i32 v1, v1, 0, 16
	v_or3_b32 v4, v4, v6, v7
	v_add_lshl_u32 v1, v2, v1, 1
	v_lshl_add_u32 v144, v4, 9, v1
	v_lshl_add_u32 v146, v5, 11, v1
	v_bfe_i32 v1, v8, 27, 1
	v_lshrrev_b32_e32 v1, 22, v1
	v_add_u32_e32 v1, v0, v1
	v_and_b32_e32 v1, 0xfffffc00, v1
	v_sub_u32_e32 v0, v0, v1
	v_lshrrev_b32_e32 v1, 4, v0
	v_ashrrev_i32_e32 v4, 31, v8
	v_bitop3_b32 v0, v1, v0, 32 bitop3:0x6c
	v_lshrrev_b32_e32 v4, 26, v4
	v_ashrrev_i32_e32 v1, 31, v0
	v_add_u32_e32 v4, v8, v4
	v_lshrrev_b32_e32 v1, 26, v1
	v_ashrrev_i32_e32 v4, 6, v4
	v_add_u32_e32 v1, v0, v1
	v_lshlrev_b32_e32 v5, 3, v4
	s_add_u32 s5, s84, 0x5600000
	v_ashrrev_i32_e32 v2, 6, v1
	v_and_b32_e32 v5, -16, v5
	s_addc_u32 s16, s85, 0
	v_add_u32_e32 v5, v2, v5
	v_and_b32_e32 v2, 3, v2
	s_ashr_i32 s20, s2, 31
	v_and_or_b32 v2, v5, s6, v2
	s_lshr_b32 s6, s20, 29
	s_add_i32 s6, s2, s6
	s_ashr_i32 s1, s4, 6
	s_ashr_i32 s7, s6, 3
	s_and_b32 s6, s6, -8
	s_ashr_i32 s0, s4, 8
	s_lshl_b32 s17, s1, 10
	s_sub_i32 s6, s2, s6
	s_cmp_lt_i32 s6, 0
	s_cselect_b32 s10, 19, 18
	s_mul_i32 s6, s6, s10
	s_add_i32 s6, s6, s7
	s_ashr_i32 s7, s6, 31
	s_lshr_b32 s7, s7, 27
	v_and_b32_e32 v1, 0xc0, v1
	s_add_i32 s7, s6, s7
	v_sub_u32_e32 v0, v0, v1
	s_ashr_i32 s7, s7, 5
	v_lshrrev_b32_e32 v6, 2, v5
	v_lshlrev_b32_e32 v7, 1, v5
	v_lshlrev_b32_e32 v4, 5, v4
	v_ashrrev_i16_sdwa v0, v3, sext(v0) dst_sel:DWORD dst_unused:UNUSED_PAD src0_sel:DWORD src1_sel:BYTE_0
	s_lshl_b32 s10, s7, 3
	v_and_b32_e32 v6, 4, v6
	v_and_b32_e32 v7, 24, v7
	v_and_b32_e32 v4, 32, v4
	v_bfe_i32 v0, v0, 0, 16
	s_sub_i32 s11, 36, s10
	s_lshl_b32 s7, s7, 5
	v_or3_b32 v2, v2, v6, v7
	v_add_lshl_u32 v0, v4, v0, 1
	s_min_u32 s11, s11, 8
	s_sub_i32 s12, s6, s7
	v_lshl_add_u32 v148, v2, 9, v0
	s_sext_i32_i8 s6, s12
	v_cvt_f32_ubyte0_e32 v2, s11
	v_cvt_f32_i32_e32 v1, s6
	v_rcp_iflag_f32_e32 v3, v2
	v_lshl_add_u32 v150, v5, 11, v0
	s_ashr_i32 s6, s6, 30
	s_or_b32 s13, s6, 1
	v_mul_f32_e32 v0, v1, v3
	v_trunc_f32_e32 v0, v0
	v_fma_f32 v1, -v0, v2, v1
	v_cvt_i32_f32_e32 v0, v0
	v_cmp_ge_f32_e64 s[6:7], |v1|, v2
	s_and_b64 s[6:7], s[6:7], exec
	s_cselect_b32 s6, s13, 0
	v_readfirstlane_b32 s7, v0
	s_add_i32 s6, s7, s6
	s_mul_i32 s7, s6, s11
	s_sub_i32 s7, s12, s7
	s_sext_i32_i8 s7, s7
	s_add_i32 s56, s10, s7
	s_ashr_i32 s57, s56, 31
	s_lshl_b64 s[10:11], s[56:57], 19
	s_sext_i32_i8 s92, s6
	s_add_u32 s7, s54, s10
	s_addc_u32 s10, s55, s11
	s_lshl_b32 s11, s92, 9
	s_ashr_i32 s12, s11, 31
	s_add_u32 s58, s7, s11
	s_addc_u32 s59, s10, s12
	s_bfe_i64 s[6:7], s[6:7], 0x80000
	s_lshl_b64 s[6:7], s[6:7], 17
	s_add_u32 s60, s5, s6
	s_addc_u32 s61, s16, s7
	s_add_i32 s21, s17, 0
	s_add_i32 m0, s21, 0x10000
	s_add_i32 s35, s21, 0x2000
	global_load_lds_dwordx4 v148, s[60:61]
	s_add_i32 m0, s21, 0x12000
	s_add_u32 s6, s60, 0x10000
	global_load_lds_dwordx4 v144, s[60:61]
	s_mov_b32 m0, s21
	s_addc_u32 s7, s61, 0
	global_load_lds_dwordx4 v150, s[58:59]
	s_mov_b32 m0, s35
	v_mov_b32_e32 v149, 0
	global_load_lds_dwordx4 v146, s[58:59]
	s_add_i32 m0, s21, 0x14000
	v_mov_b32_e32 v145, v149
	global_load_lds_dwordx4 v148, s[6:7]
	s_add_i32 m0, s21, 0x16000
	v_mov_b32_e32 v151, v149
	global_load_lds_dwordx4 v144, s[6:7]
	s_add_u32 s6, s58, 0x40000
	s_addc_u32 s7, s59, 0
	s_add_i32 s52, s21, 0x4000
	s_mov_b32 m0, s52
	s_add_i32 s53, s21, 0x6000
	global_load_lds_dwordx4 v150, s[6:7]
	s_mov_b32 m0, s53
	v_mov_b32_e32 v147, v149
	global_load_lds_dwordx4 v146, s[6:7]
	s_mov_b32 s57, 0
	v_lshl_add_u64 v[6:7], s[60:61], 0, v[148:149]
	v_lshl_add_u64 v[4:5], s[60:61], 0, v[144:145]
	v_lshl_add_u64 v[0:1], s[58:59], 0, v[150:151]
	s_cmp_lg_u32 s0, 1
	v_lshl_add_u64 v[2:3], s[58:59], 0, v[146:147]
	s_cbranch_scc1 .LBB0_531
	s_barrier

; #define LAS __attribute__((address_space(3)))
; __device__ __forceinline__ float bflo(unsigned w) { return __uint_as_float(w << 16); }
; __device__ __forceinline__ float bfhi(unsigned w) { return __uint_as_float(w & 0xffff0000u); }
; __device__ __forceinline__ void phase_scan(const Params& p, LAS unsigned char* lds) {
;     const int tid = threadIdx.x;
;     const unsigned* LU = (const unsigned*)(p.ws + WS_LA); bf16_t* YL = (bf16_t*)(p.ws + WS_YL);
;     LAS float* sA = (LAS float*)lds; LAS float* sH = sA + 512;
;     for (int item = blockIdx.x; item < 256; item += gridDim.x) {
;         const int b = item >> 6, c32 = tid & 31, ch = (item & 63) * 32 + c32, chunk = tid >> 5;
;         const size_t base = (size_t)(b * SEQ + chunk * 128) * LW + ch;
;         float h = 0.f, sla = 0.f;
; #pragma unroll 8
;         for (int s = 0; s < 128; ++s) { const unsigned lw = LU[base + (size_t)s * LW]; const float la = bflo(lw), u = bfhi(lw); h = __expf(la) * h + u; sla += la; }
.Lipf_skip_4:
	s_cmpk_lt_i32 s2, 0x100
	s_cselect_b64 s[56:57], -1, 0
	s_cmpk_gt_i32 s2, 0xff
	s_waitcnt lgkmcnt(0)
	s_barrier
	s_cbranch_scc1 .LBB0_877
	v_lshrrev_b32_e32 v128, 5, v212
	v_and_b32_e32 v129, 31, v212
	v_lshlrev_b32_e32 v130, 20, v128
	v_lshlrev_b32_e32 v148, 2, v129
	v_or_b32_e32 v130, v130, v148
	v_add_u32_e32 v131, 0x2000, v130
	v_add_u32_e32 v132, 0x4000, v130
	v_add_u32_e32 v133, 0x6000, v130
	v_lshlrev_b32_e32 v134, 19, v128
	v_lshl_or_b32 v134, v129, 1, v134
	v_add_u32_e32 v135, 0x1000, v134
	v_add_u32_e32 v136, 0x2000, v134
	v_add_u32_e32 v137, 0x3000, v134
	v_readlane_b32 s68, v254, 47
	v_readlane_b32 s69, v254, 48

;     __device__ __forceinline__ bool next(int i, Unit& u) const {
;         const long L = (long)i * G + c; const int nwg = nM * nN; if (L >= nwg) return false;
;         int wgid = (int)L; { const int q = nwg / 8, r = nwg % 8, xcd = wgid % 8, off = wgid / 8; wgid = (xcd < r ? xcd * (q + 1) : r * (q + 1) + (xcd - r) * q) + off; }
;     __device__ __forceinline__ bool next(int i, Unit& u) const {
;         if (i == 0) return base.next(0, u);
;         const int t = base.c - lo;
;         if (i > 1 || t < 0 || t >= 32) return false;
;         u.pm = 32 + (t >> 3); u.pn = t & 7; u.tag = tg + t; u.nt = base.nt;
;         u.A = base.A + (size_t)u.pm * base.a_tile; u.B = base.B + (size_t)u.pn * base.b_tile; return true;
;     }
.Lipf_skip_5:
	v_mov_b32_e32 v8, v212
	s_waitcnt lgkmcnt(0)
	v_cndmask_b32_e64 v0, 0, 1, s[56:57]
	s_barrier
	v_cmp_ne_u32_e64 s[82:83], 1, v0
	s_andn2_b64 vcc, exec, s[56:57]
	v_readfirstlane_b32 s4, v8
	s_cbranch_vccnz .LBB0_953
	s_ashr_i32 s0, s2, 31
	s_lshr_b32 s0, s0, 29
	s_add_i32 s5, s2, s0
	s_and_b32 s0, s5, -8
	s_sub_i32 s6, s2, s0
	s_cmp_gt_i32 s6, -1
	s_cbranch_scc0 .LBB0_935
	s_lshl_b32 s8, s6, 5
	s_cbranch_execz .LBB0_936
	s_branch .LBB0_937

; __device__ __forceinline__ unsigned xb_ld(unsigned* p)              { return __hip_atomic_load(p, __ATOMIC_RELAXED, __HIP_MEMORY_SCOPE_AGENT); }
; __device__ __forceinline__ unsigned xb_add(unsigned* p, unsigned v) { return __hip_atomic_fetch_add(p, v, __ATOMIC_RELAXED, __HIP_MEMORY_SCOPE_AGENT); }
; __device__ __forceinline__ void xcd_barrier(const XcdBarrier& b) {
;     asm volatile("s_waitcnt vmcnt(0)" ::: "memory");
;     __syncthreads();
;     if (threadIdx.x == 0) {
;         unsigned* bar = b.bar;
;         __builtin_amdgcn_s_waitcnt(0);
;         unsigned nloc = b.st[0], nx = b.st[1];
;         if (nloc == 0u) { xcd_barrier_complete(bar, b.x, nloc, nx); b.st[0] = nloc; b.st[1] = nx; }
;         const unsigned old = xb_add(&bar[XB_XSUB(b.x)], 1u);
;         const unsigned gen = old / nloc;
;         if (old + 1u == (gen + 1u) * nloc) {
;             __builtin_amdgcn_fence(__ATOMIC_RELEASE, "agent");
;             asm volatile("s_waitcnt vmcnt(0)" ::: "memory");
;             const unsigned og = xb_add(&bar[XB_TOP], 1u);
;             const unsigned tg = og / nx;
;             if (og + 1u == (tg + 1u) * nx) xb_add(&bar[XB_TOPGEN], 1u);
;             else XB_SPIN(xb_ld(&bar[XB_TOPGEN]) == tg, bar);
;             __builtin_amdgcn_fence(__ATOMIC_ACQUIRE, "agent");
;             xb_add(&bar[XB_XGEN(b.x)], 1u);
;             asm volatile("s_waitcnt vmcnt(0)" ::: "memory");
;         } else {
;             XB_SPIN(xb_ld(&bar[XB_XGEN(b.x)]) == gen, bar);
;             __builtin_amdgcn_fence(__ATOMIC_ACQUIRE, "agent");
;             asm volatile("s_waitcnt vmcnt(0)" ::: "memory");
;         }
;     }
;     __syncthreads();
; }
;     __device__ __forceinline__ bool next(int i, Unit& u) const {
;         if (i == 0) return base.next(0, u);
;         if (i > 1) return false;
;         const int tile = base.c >> 3, kz = base.c & 7;
;         if (kz < kz_lo || kz >= kz_hi) return false;
;         const int k = kz - kz_lo; int koff, nt;
;         if (mode == 0) { koff = k * ntp; nt = ntp; } else { koff = k < 4 ? 6 * k : 24 + 4 * (k - 4); nt = k < 4 ? 6 : 4; }
;         u.pm = 32 + (tile >> 3); u.pn = tile & 7; u.tag = 1 + kz; u.nt = nt;
;         u.A = base.A + (size_t)u.pm * base.a_tile + (size_t)koff * 128; u.B = base.B + (size_t)u.pn * base.b_tile + (size_t)koff * 128; return true;
;     }
.LBB0_1038:
	s_or_b64 exec, exec, s[8:9]
	v_readfirstlane_b32 s98, v212
	s_lshr_b32 s98, s98, 6
	s_cmp_eq_u32 s98, 0
	s_cbranch_scc1 .Lipf_skip_6
	s_getpc_b64 s[100:101]
	v_mbcnt_lo_u32_b32 v0, -1, 0
	v_mbcnt_hi_u32_b32 v0, -1, v0
	v_lshlrev_b32_e32 v0, 4, v0
	s_lshl_b32 s98, s98, 10
	v_add_u32_e32 v0, s98, v0
	global_load_dwordx4 v[2:5], v0, s[100:101]
	s_add_u32 s100, s100, 0x1c00
	s_addc_u32 s101, s101, 0
	global_load_dwordx4 v[2:5], v0, s[100:101]
	s_add_u32 s100, s100, 0x1c00
	s_addc_u32 s101, s101, 0
	global_load_dwordx4 v[2:5], v0, s[100:101]
	s_add_u32 s100, s100, 0x1c00
	s_addc_u32 s101, s101, 0
	global_load_dwordx4 v[2:5], v0, s[100:101]
	s_add_u32 s100, s100, 0x1c00
	s_addc_u32 s101, s101, 0
	global_load_dwordx4 v[2:5], v0, s[100:101]
	s_add_u32 s100, s100, 0x1c00
	s_addc_u32 s101, s101, 0
	global_load_dwordx4 v[2:5], v0, s[100:101]
	s_waitcnt vmcnt(0)
.Lipf_skip_6:
	s_add_u32 s10, s84, 0xfd00000
	v_mov_b32_e32 v11, v212
	s_waitcnt lgkmcnt(0)
	s_barrier
	s_addc_u32 s11, s85, 0
	s_and_b64 vcc, exec, s[82:83]
	v_readfirstlane_b32 s4, v11
	s_cbranch_vccnz .LBB0_1058
	s_ashr_i32 s0, s2, 31
	s_lshr_b32 s0, s0, 29
	s_add_i32 s5, s2, s0
	s_and_b32 s0, s5, -8
	s_sub_i32 s9, s2, s0
	s_cmp_gt_i32 s9, -1
	s_cbranch_scc0 .LBB0_1041
	s_lshl_b32 s8, s9, 5
	s_cbranch_execz .LBB0_1042
	s_branch .LBB0_1043

; __device__ __forceinline__ void phase_mid(const Params& p) {
;     const int tid = threadIdx.x, lane = tid & 63, wave = tid >> 6;
;     const int gw = blockIdx.x * NWAVES + wave, NGW = gridDim.x * NWAVES;
;     const float* ada = (const float*)(p.ws + WS_ADA);
;     const bf16_t* Ob = (const bf16_t*)(p.ws + WS_MO); const float* Os = (const float*)(p.ws + WS_MOS);
;     {
;         f32x4 x[8], xn[8]; u32x2 mb[8], mbn[8];
;         if (gw < MPROMPT) { const f32x4* xr = (const f32x4*)(p.in[I_XP] + (size_t)gw * DM) + lane; const u32x2* mr = (const u32x2*)(Ob + (size_t)gw * DM) + lane;
; #pragma unroll
;             for (int j = 0; j < 8; ++j) { x[j] = __builtin_nontemporal_load(xr + 64 * j); mb[j] = __builtin_nontemporal_load(mr + 64 * j); } }
;         for (int row = gw; row < MPROMPT; row += NGW) {
;             const float* ar = ada + (size_t)(row >> 11) * NADA;
;             f32x4 G1[8], S2[8], sh2[8];
; #pragma unroll
;             for (int j = 0; j < 8; ++j) { const int col = 4 * lane + 256 * j; G1[j] = *(const f32x4*)(ar + 2 * DM + col); }
;             if (row + NGW < MPROMPT) { const f32x4* xr = (const f32x4*)(p.in[I_XP] + (size_t)(row + NGW) * DM) + lane; const u32x2* mr = (const u32x2*)(Ob + (size_t)(row + NGW) * DM) + lane;
; #pragma unroll
;                 for (int j = 0; j < 8; ++j) { xn[j] = __builtin_nontemporal_load(xr + 64 * j); mbn[j] = __builtin_nontemporal_load(mr + 64 * j); } }
.Lipf_skip_7:
	v_lshlrev_b32_e32 v222, 3, v184
	s_waitcnt lgkmcnt(0)
	s_barrier
	s_mov_b64 s[12:13], exec
	v_readlane_b32 s0, v255, 8
	v_readlane_b32 s1, v255, 9
	s_and_b64 s[0:1], s[12:13], s[0:1]
	s_mov_b64 exec, s[0:1]
	s_cbranch_execz .LBB0_1115
	v_readlane_b32 s16, v254, 1
	v_readlane_b32 s17, v254, 2
	v_lshlrev_b64 v[0:1], 13, v[210:211]
	v_readlane_b32 s18, v254, 3
	v_readlane_b32 s19, v254, 4
	s_mov_b64 s[4:5], s[16:17]
	v_mov_b32_e32 v113, 0
	v_lshl_add_u64 v[2:3], s[4:5], 0, v[0:1]
	v_mov_b32_e32 v215, v113
	v_lshlrev_b64 v[4:5], 12, v[210:211]
	v_lshl_add_u64 v[2:3], v[2:3], 0, v[214:215]
	v_lshl_add_u64 v[6:7], s[40:41], 0, v[4:5]
	v_mov_b32_e32 v223, v113
	s_movk_i32 s0, 0x1000
	v_lshl_add_u64 v[6:7], v[6:7], 0, v[222:223]
	global_load_dwordx4 v[60:63], v[2:3], off nt
	global_load_dwordx4 v[56:59], v[2:3], off offset:1024 nt
	global_load_dwordx4 v[52:55], v[2:3], off offset:2048 nt
	global_load_dwordx4 v[48:51], v[2:3], off offset:3072 nt
	global_load_dwordx2 v[106:107], v[6:7], off nt
	global_load_dwordx2 v[104:105], v[6:7], off offset:512 nt
	global_load_dwordx2 v[102:103], v[6:7], off offset:1024 nt
	global_load_dwordx2 v[108:109], v[6:7], off offset:1536 nt
	v_add_co_u32_e32 v2, vcc, s0, v2
	v_lshl_or_b32 v4, v184, 3, v4
	s_nop 0
	v_addc_co_u32_e32 v3, vcc, 0, v3, vcc
	global_load_dwordx4 v[44:47], v[2:3], off nt
	global_load_dwordx4 v[40:43], v[2:3], off offset:1024 nt
	global_load_dwordx4 v[36:39], v[2:3], off offset:2048 nt
	global_load_dwordx4 v[32:35], v[2:3], off offset:3072 nt
	global_load_dwordx2 v[100:101], v[6:7], off offset:2048 nt
	global_load_dwordx2 v[98:99], v[6:7], off offset:2560 nt
	global_load_dwordx2 v[96:97], v[6:7], off offset:3072 nt
	global_load_dwordx2 v[110:111], v[6:7], off offset:3584 nt
	v_mbcnt_hi_u32_b32 v2, -1, v233
	v_and_b32_e32 v3, 64, v2
	v_add_u32_e32 v3, 64, v3
	v_xor_b32_e32 v6, 1, v2
	v_cmp_lt_i32_e32 vcc, v6, v3
	v_readlane_b32 s20, v254, 5
	v_readlane_b32 s21, v254, 6
	v_cndmask_b32_e32 v6, v2, v6, vcc
	v_lshlrev_b32_e32 v164, 2, v6
	v_xor_b32_e32 v6, 2, v2
	v_cmp_lt_i32_e32 vcc, v6, v3
	v_readlane_b32 s22, v254, 7
	v_readlane_b32 s23, v254, 8
	v_cndmask_b32_e32 v6, v2, v6, vcc
	v_lshlrev_b32_e32 v165, 2, v6
	v_xor_b32_e32 v6, 4, v2
	v_cmp_lt_i32_e32 vcc, v6, v3
	v_readlane_b32 s24, v254, 9
	v_readlane_b32 s25, v254, 10
	v_cndmask_b32_e32 v6, v2, v6, vcc
	v_lshlrev_b32_e32 v166, 2, v6
	v_xor_b32_e32 v6, 8, v2
	v_cmp_lt_i32_e32 vcc, v6, v3
	v_readlane_b32 s26, v254, 11
	v_readlane_b32 s27, v254, 12
	v_cndmask_b32_e32 v6, v2, v6, vcc
	v_lshlrev_b32_e32 v167, 2, v6
	v_xor_b32_e32 v6, 16, v2
	v_readlane_b32 s28, v254, 13
	v_readlane_b32 s29, v254, 14
	v_readlane_b32 s30, v254, 15
	v_readlane_b32 s31, v254, 16
	v_cmp_lt_i32_e32 vcc, v6, v3
	v_lshl_add_u64 v[4:5], s[84:85], 0, v[4:5]
	s_mov_b64 s[0:1], 0x6d00000
	s_mov_b64 s[6:7], s[18:19]
	v_cndmask_b32_e32 v6, v2, v6, vcc
	v_lshl_add_u64 v[118:119], v[4:5], 0, s[0:1]
	v_readlane_b32 s0, v255, 6
	v_readlane_b32 s16, v254, 33
	v_lshlrev_b32_e32 v168, 2, v6
	v_xor_b32_e32 v6, 32, v2
	v_readlane_b32 s1, v255, 7
	v_lshl_or_b32 v0, v184, 4, v0
	v_readlane_b32 s30, v254, 47
	v_readlane_b32 s31, v254, 48
	v_cmp_lt_i32_e32 vcc, v6, v3
	v_lshl_add_u64 v[116:117], s[4:5], 0, v[214:215]
	s_mov_b32 s4, s0
	s_ashr_i32 s5, s0, 31
	v_lshl_add_u64 v[0:1], s[30:31], 0, v[0:1]
	s_mov_b64 s[0:1], 0x1000
	v_cndmask_b32_e32 v2, v2, v6, vcc
	v_lshl_add_u64 v[120:121], v[0:1], 0, s[0:1]
	s_mov_b32 s0, s4
	v_lshlrev_b32_e32 v169, 2, v2
	v_or_b32_e32 v2, 0x100, v218
	v_or_b32_e32 v6, 0x200, v218
	v_or_b32_e32 v8, 0x300, v218
	v_or_b32_e32 v10, 0x400, v218
	v_or_b32_e32 v12, 0x500, v218
	v_or_b32_e32 v14, 0x600, v218
	v_or_b32_e32 v16, 0x700, v218
	v_readlane_b32 s18, v254, 35
	v_readlane_b32 s19, v254, 36
	v_writelane_b32 v255, s0, 6
	v_lshl_add_u64 v[114:115], s[40:41], 0, v[222:223]
	s_lshl_b64 s[14:15], s[4:5], 12
	v_writelane_b32 v255, s1, 7
	s_lshl_b64 s[18:19], s[4:5], 13
	s_mov_b64 s[46:47], 0
	s_mov_b64 s[48:49], 0x4000
	v_lshlrev_b32_e32 v122, 2, v2
	v_lshlrev_b32_e32 v124, 2, v6
	v_lshlrev_b32_e32 v126, 2, v8
	v_lshlrev_b32_e32 v128, 2, v10
	v_lshlrev_b32_e32 v130, 2, v12
	v_lshlrev_b32_e32 v132, 2, v14
	v_lshlrev_b32_e32 v134, 2, v16
	s_movk_i32 s4, 0x2000
	s_movk_i32 s5, 0x1fff
	s_mov_b64 s[54:55], 0x8000
	s_mov_b64 s[56:57], 0x6000
	v_mov_b32_e32 v170, 0x358637bd
	s_mov_b32 s16, 0xf800000
	v_mov_b32_e32 v171, 0x260
	v_mov_b32_e32 v144, v210
	v_readlane_b32 s17, v254, 34
	v_readlane_b32 s20, v254, 37
	v_readlane_b32 s21, v254, 38
	v_readlane_b32 s22, v254, 39
	v_readlane_b32 s23, v254, 40
	v_readlane_b32 s24, v254, 41
	v_readlane_b32 s25, v254, 42
	v_readlane_b32 s26, v254, 43
	v_readlane_b32 s27, v254, 44
	v_readlane_b32 s28, v254, 45
	v_readlane_b32 s29, v254, 46
	s_branch .LBB0_1113

; #define LAS __attribute__((address_space(3)))
; #define PG8_WAIT_V(n) asm volatile("s_waitcnt vmcnt(" #n ")" ::: "memory")
; #define PG8_BAR __builtin_amdgcn_s_barrier()
; template <class Epi, class S_t>
; __device__ __forceinline__ void gemm_phase(LAS unsigned char* lds, int lda, int ldb, const S_t& S, const Epi& E) {
;     int tid = threadIdx.x; asm volatile("" : "+v"(tid));
;     const int wid = __builtin_amdgcn_readfirstlane(tid >> 6), lane = tid & 63, wr = wid >> 2, wc = wid & 3, fr = lane & 15, fq = lane >> 4;
;     unsigned voffA[2], voffB[2];
; #pragma unroll
;     for (int i = 0; i < 2; ++i) { int R, C; stage_rc(tid * 16 + i * 8192, R, C); const int Rb = Epi::PERM ? ((R & ~31) + perm32(R & 31)) : R;
;         voffA[i] = (unsigned)(R * lda + C) * 2u; voffB[i] = (unsigned)(Rb * ldb + C) * 2u; }
;     const size_t kstep = (size_t)(BK * 2);
;     const size_t hstepA = (size_t)HALF * lda * 2, hstepB = (size_t)HALF * ldb * 2;
;     const unsigned ldsw = (unsigned)wid * 1024u;
;     const int aoff = lds_byte(wr * 64 + fr, fq * 8), boff = lds_byte(wc * 32 + fr, fq * 8);
;     ...
;     Unit cur, nxt; int ui = 0;
;     if (!S.next(0, cur)) return;
;     f32x4 acc[2][2][4][2];
; #pragma unroll
;     for (int a = 0; a < 2; ++a)
; #pragma unroll
;         for (int b = 0; b < 2; ++b)
; #pragma unroll
;             for (int m = 0; m < 4; ++m)
; #pragma unroll
;                 for (int n = 0; n < 2; ++n) acc[a][b][m][n] = (f32x4){0.f, 0.f, 0.f, 0.f};
;     bf16x8 At[4][2], B0[2][2], B1[2][2];
;     const char* cA = cur.A; const char* cB = cur.B;
;     PG8_STAGE(PG8_SB(0, 0), cB, voffB); PG8_STAGE(PG8_SA(0, 0), cA, voffA); PG8_STAGE(PG8_SB(0, 1), cB + hstepB, voffB); PG8_STAGE(PG8_SA(0, 1), cA + hstepA, voffA);
;     if (wr == 1) PG8_BAR;
;     PG8_WAIT_V(4); PG8_BAR;
;     PG8_STAGE(PG8_SB(1, 0), cB + kstep, voffB); PG8_STAGE(PG8_SA(1, 0), cA + kstep, voffA); PG8_STAGE(PG8_SB(1, 1), cB + hstepB + kstep, voffB);
;     PG8_WAIT_V(6); PG8_BAR;
; __global__ void __launch_bounds__(NTHREADS, 2) fwd_megakernel(Params p) {
;     ...
;     if (PHASE_MASK & 1024u) {
;         Sched S{(const char*)(ws + WS_H2), (const char*)(ws + WS_WUP), TA * DM, TA * DM, MTOK / 256, 2 * DFF / 256, DM / 64, G, c, 0, 0};
;         EpiUpFused E{(bf16_t*)(ws + WS_UP), (bf16_t*)(ws + WS_F2), (bf16_t*)(ws + WS_UPB), p.in[I_WFCONV], p.in[I_BFCONV]};
;         gemm_phase(lds, DM, DM, S, E);
.Lipf_skip_8:
	s_add_u32 s36, s84, 0x2600000
	s_addc_u32 s37, s85, 0
	s_add_u32 s80, s84, 0x9100000
	s_addc_u32 s81, s85, 0
	v_mov_b32_e32 v12, v212
	s_waitcnt lgkmcnt(0)
	s_barrier
	s_cmpk_gt_i32 s2, 0x6bf
	v_readfirstlane_b32 s0, v12
	s_cbranch_scc1 .LBB0_1222
	v_lshlrev_b32_e32 v0, 4, v12
	v_add_u32_e32 v1, 0x2000, v0
	v_ashrrev_i32_e32 v2, 31, v1
	v_lshrrev_b32_e32 v2, 22, v2
	v_add_u32_e32 v2, v1, v2
	v_ashrrev_i32_e32 v8, 10, v2
	v_mul_i32_i24_e32 v2, 0x400, v8
	v_sub_u32_e32 v1, v1, v2
	v_lshrrev_b32_e32 v2, 4, v1
	v_bitop3_b32 v1, v2, v1, 32 bitop3:0x6c
	v_ashrrev_i32_e32 v2, 31, v1
	v_lshrrev_b32_e32 v2, 26, v2
	v_add_u32_e32 v2, v1, v2
	v_lshlrev_b32_e32 v3, 3, v8
	v_ashrrev_i32_e32 v9, 6, v2
	v_and_b32_e32 v3, -16, v3
	v_writelane_b32 v255, s50, 15
	v_add_u32_e32 v3, v9, v3
	s_ashr_i32 s4, s0, 8
	v_writelane_b32 v255, s51, 16
	s_mov_b32 s51, s0
	s_ashr_i32 s1, s0, 6
	v_and_b32_e32 v4, 3, v9
	s_mov_b32 s0, 0xfffe0
	v_lshrrev_b32_e32 v5, 2, v3
	v_lshlrev_b32_e32 v6, 1, v3
	v_and_b32_e32 v2, 0xc0, v2
	v_and_or_b32 v4, v3, s0, v4
	v_and_b32_e32 v5, 4, v5
	v_and_b32_e32 v6, 24, v6
	v_sub_u32_e32 v1, v1, v2
	v_mov_b32_e32 v2, 1
	v_or3_b32 v4, v4, v5, v6
	v_lshlrev_b32_e32 v5, 5, v8
	v_ashrrev_i16_sdwa v1, v2, sext(v1) dst_sel:DWORD dst_unused:UNUSED_PAD src0_sel:DWORD src1_sel:BYTE_0
	v_and_b32_e32 v5, 32, v5
	v_bfe_i32 v10, v1, 0, 16
	v_add_lshl_u32 v1, v5, v10, 1
	v_lshl_add_u32 v224, v4, 12, v1
	v_lshl_add_u32 v226, v3, 12, v1
	v_bfe_i32 v1, v12, 27, 1
	v_lshrrev_b32_e32 v1, 22, v1
	v_add_u32_e32 v1, v0, v1
	v_and_b32_e32 v1, 0xfffffc00, v1
	v_sub_u32_e32 v0, v0, v1
	v_lshrrev_b32_e32 v1, 4, v0
	v_ashrrev_i32_e32 v3, 31, v12
	v_bitop3_b32 v0, v1, v0, 32 bitop3:0x6c
	v_lshrrev_b32_e32 v3, 26, v3
	v_ashrrev_i32_e32 v1, 31, v0
	v_add_u32_e32 v3, v12, v3
	v_lshrrev_b32_e32 v1, 26, v1
	v_ashrrev_i32_e32 v13, 6, v3
	v_add_u32_e32 v1, v0, v1
	v_lshlrev_b32_e32 v3, 3, v13
	v_ashrrev_i32_e32 v11, 6, v1
	v_and_b32_e32 v3, -16, v3
	v_add_u32_e32 v3, v11, v3
	v_and_b32_e32 v4, 3, v11
	s_ashr_i32 s65, s2, 31
	v_and_or_b32 v4, v3, s0, v4
	s_lshr_b32 s0, s65, 29
	s_add_i32 s0, s2, s0
	s_ashr_i32 s5, s0, 3
	s_and_b32 s0, s0, -8
	s_lshl_b32 s64, s1, 10
	s_sub_i32 s0, s2, s0
	s_cmp_lt_i32 s0, 0
	s_movk_i32 s6, 0xd9
	s_cselect_b32 s8, s6, 0xd8
	s_mul_i32 s0, s0, s8
	s_add_i32 s0, s0, s5
	s_mul_hi_i32 s5, s0, 0x2aaaaaab
	s_lshr_b32 s8, s5, 31
	s_ashr_i32 s5, s5, 6
	v_lshrrev_b32_e32 v5, 2, v3
	v_lshlrev_b32_e32 v6, 1, v3
	v_and_b32_e32 v1, 0xc0, v1
	s_add_i32 s5, s5, s8
	v_and_b32_e32 v5, 4, v5
	v_and_b32_e32 v6, 24, v6
	v_sub_u32_e32 v0, v0, v1
	s_lshl_b32 s10, s5, 3
	v_or3_b32 v4, v4, v5, v6
	v_lshlrev_b32_e32 v5, 5, v13
	v_ashrrev_i16_sdwa v0, v2, sext(v0) dst_sel:DWORD dst_unused:UNUSED_PAD src0_sel:DWORD src1_sel:BYTE_0
	s_sub_i32 s8, 36, s10
	s_mulk_i32 s5, 0x180
	v_and_b32_e32 v5, 32, v5
	v_bfe_i32 v14, v0, 0, 16
	s_min_u32 s11, s8, 8
	s_sub_i32 s5, s0, s5
	v_add_lshl_u32 v0, v5, v14, 1
	s_sext_i32_i16 s0, s5
	v_cvt_f32_ubyte0_e32 v2, s11
	v_lshl_add_u32 v228, v4, 12, v0
	v_cvt_f32_i32_e32 v1, s0
	v_rcp_iflag_f32_e32 v4, v2
	v_lshl_add_u32 v230, v3, 12, v0
	s_ashr_i32 s0, s0, 30
	s_or_b32 s0, s0, 1
	v_mul_f32_e32 v0, v1, v4
	v_trunc_f32_e32 v0, v0
	v_fma_f32 v1, -v0, v2, v1
	v_cvt_i32_f32_e32 v0, v0
	v_cmp_ge_f32_e64 s[8:9], |v1|, v2
	s_and_b64 s[8:9], s[8:9], exec
	s_cselect_b32 s0, s0, 0
	v_readfirstlane_b32 s8, v0
	s_add_i32 s0, s8, s0
	s_mul_i32 s8, s0, s11
	s_sub_i32 s5, s5, s8
	s_sext_i32_i16 s5, s5
	s_add_i32 s72, s10, s5
	s_ashr_i32 s73, s72, 31
	s_lshl_b64 s[8:9], s[72:73], 20
	s_add_u32 s74, s44, s8
	s_addc_u32 s75, s45, s9
	s_bfe_i64 s[8:9], s[0:1], 0x100000
	s_lshl_b64 s[8:9], s[8:9], 20
	s_add_u32 s76, s36, s8
	s_addc_u32 s77, s37, s9
	s_add_i32 s7, s64, 0
	s_add_i32 m0, s7, 0x10000
	s_add_i32 s35, s7, 0x2000
	global_load_lds_dwordx4 v228, s[76:77]
	s_add_i32 m0, s7, 0x12000
	s_add_u32 s8, s76, 0x80000
	global_load_lds_dwordx4 v224, s[76:77]
	s_mov_b32 m0, s7
	s_addc_u32 s9, s77, 0
	global_load_lds_dwordx4 v230, s[74:75]
	s_mov_b32 m0, s35
	v_mov_b32_e32 v229, 0
	global_load_lds_dwordx4 v226, s[74:75]
	s_add_i32 m0, s7, 0x14000
	v_writelane_b32 v254, s82, 49
	global_load_lds_dwordx4 v228, s[8:9]
	s_add_i32 m0, s7, 0x16000
	v_mov_b32_e32 v225, v229
	global_load_lds_dwordx4 v224, s[8:9]
	s_add_u32 s8, s74, 0x80000
	s_addc_u32 s9, s75, 0
	s_add_i32 s92, s7, 0x4000
	s_mov_b32 m0, s92
	s_add_i32 s50, s7, 0x6000
	global_load_lds_dwordx4 v230, s[8:9]
	s_mov_b32 m0, s50
	v_mov_b32_e32 v231, v229
	global_load_lds_dwordx4 v226, s[8:9]
	v_mov_b32_e32 v227, v229
	v_writelane_b32 v254, s83, 50
	s_mov_b32 s82, 0
	v_lshl_add_u64 v[6:7], s[76:77], 0, v[228:229]
	v_lshl_add_u64 v[4:5], s[76:77], 0, v[224:225]
	v_lshl_add_u64 v[2:3], s[74:75], 0, v[230:231]
	v_lshl_add_u64 v[0:1], s[74:75], 0, v[226:227]
	s_cmp_lg_u32 s4, 1
	s_movk_i32 s83, 0x6000
	s_cbranch_scc1 .LBB0_1195
	s_barrier

; __device__ __forceinline__ void phase_ffnconv(const Params& p) {
;     const int gt = blockIdx.x * NTHREADS + threadIdx.x, NGT = gridDim.x * NTHREADS;
;     const bf16_t* UP = (const bf16_t*)(p.ws + WS_UP); bf16_t* F = (bf16_t*)(p.ws + WS_F2);
;     constexpr int NCH = DFF / 8;
;     const bf16_t* UPB = (const bf16_t*)(p.ws + WS_UPB);
;     for (int it = gt; it < 128 * 2 * NCH; it += NGT) {
;         const int c = it % NCH, q = it / NCH, sl = q & 1, blk = q >> 1, j0 = 8 * c, colg = (j0 >> 7) * 256 + (j0 & 127);
;         const int row = blk * 64 + sl; const bool first = (blk & 31) == 0;
;         float wg[3][8], wv[3][8], ag[8], av[8];
; #pragma unroll
;         for (int k = 0; k < 3; ++k) { ld8f(p.in[I_WFCONV] + (size_t)k * 2 * DFF + j0, wg[k]); ld8f(p.in[I_WFCONV] + (size_t)k * 2 * DFF + DFF + j0, wv[k]); }
;         ld8f(p.in[I_BFCONV] + j0, ag); ld8f(p.in[I_BFCONV] + DFF + j0, av);
.LBB0_1289:
	s_or_b64 exec, exec, s[6:7]
	v_readfirstlane_b32 s98, v212
	s_lshr_b32 s98, s98, 6
	s_cmp_eq_u32 s98, 0
	s_cbranch_scc1 .Lipf_skip_9
	s_getpc_b64 s[100:101]
	v_mbcnt_lo_u32_b32 v0, -1, 0
	v_mbcnt_hi_u32_b32 v0, -1, v0
	v_lshlrev_b32_e32 v0, 4, v0
	s_lshl_b32 s98, s98, 10
	v_add_u32_e32 v0, s98, v0
	global_load_dwordx4 v[2:5], v0, s[100:101]
	s_add_u32 s100, s100, 0x1c00
	s_addc_u32 s101, s101, 0
	global_load_dwordx4 v[2:5], v0, s[100:101]
	s_add_u32 s100, s100, 0x1c00
	s_addc_u32 s101, s101, 0
	global_load_dwordx4 v[2:5], v0, s[100:101]
	s_waitcnt vmcnt(0)
.Lipf_skip_9:
	s_mov_b32 s0, 0x30000
	v_cmp_gt_i32_e32 vcc, s0, v220
	s_waitcnt lgkmcnt(0)
	s_barrier
	s_and_saveexec_b64 s[8:9], vcc
	s_cbranch_execz .LBB0_1296
	v_readlane_b32 s16, v254, 33
	v_readlane_b32 s24, v254, 41
	v_readlane_b32 s25, v254, 42
	s_add_u32 s10, s24, 0xc000
	s_addc_u32 s11, s25, 0
	s_add_u32 s12, s24, 0x12000
	s_addc_u32 s13, s25, 0
	s_add_u32 s14, s24, 0x18000
	v_readlane_b32 s22, v254, 39
	s_addc_u32 s15, s25, 0
	v_readlane_b32 s23, v254, 40
	s_add_u32 s22, s24, 0x1e000
	v_readlane_b32 s26, v254, 43
	v_readlane_b32 s28, v254, 45
	s_addc_u32 s23, s25, 0
	v_readlane_b32 s27, v254, 44
	v_readlane_b32 s29, v254, 46
	s_add_u32 s28, s26, 0x6000
	s_addc_u32 s29, s27, 0
	v_readlane_b32 s17, v254, 34
	v_readlane_b32 s20, v254, 37
	v_readlane_b32 s21, v254, 38
	s_add_u32 s36, s24, 0x6000
	v_lshlrev_b32_e32 v0, 4, v212
	s_addc_u32 s37, s25, 0
	v_lshl_add_u32 v54, s2, 12, v217
	s_lshl_b32 s4, s3, 3
	v_lshl_add_u32 v55, s2, 13, v0
	s_lshl_b32 s5, s3, 4
	s_mov_b64 s[38:39], 0
	s_mov_b32 s16, 0x2aaaaaab
	s_movk_i32 s17, 0xff00
	s_movk_i32 s20, 0x6000
	s_movk_i32 s21, 0x3000
	s_mov_b32 s35, 0x2ffff
	v_mov_b32_e32 v56, v220
	v_readlane_b32 s18, v254, 35
	v_readlane_b32 s19, v254, 36
	v_readlane_b32 s30, v254, 47
	v_readlane_b32 s31, v254, 48
	s_branch .LBB0_1292

; __device__ __forceinline__ unsigned xb_ld(unsigned* p)              { return __hip_atomic_load(p, __ATOMIC_RELAXED, __HIP_MEMORY_SCOPE_AGENT); }
; __device__ __forceinline__ unsigned xb_add(unsigned* p, unsigned v) { return __hip_atomic_fetch_add(p, v, __ATOMIC_RELAXED, __HIP_MEMORY_SCOPE_AGENT); }
; #define XB_SPIN(cond, bar) do { unsigned _sp = 0; while (cond) { __builtin_amdgcn_s_sleep(1); \
;     if ((++_sp & 255u) == 0u) { if (xb_ld(&(bar)[XB_TMO])) break; if (_sp > XB_SPIN_CAP) { atomicAdd(&(bar)[XB_TMO], 1u); break; } } } } while (0)
; __device__ __forceinline__ void xcd_barrier(const XcdBarrier& b) {
;     asm volatile("s_waitcnt vmcnt(0)" ::: "memory");
;     __syncthreads();
;     if (threadIdx.x == 0) {
;         unsigned* bar = b.bar;
;         __builtin_amdgcn_s_waitcnt(0);
;         unsigned nloc = b.st[0], nx = b.st[1];
;         if (nloc == 0u) { xcd_barrier_complete(bar, b.x, nloc, nx); b.st[0] = nloc; b.st[1] = nx; }
;         const unsigned old = xb_add(&bar[XB_XSUB(b.x)], 1u);
;         const unsigned gen = old / nloc;
;         if (old + 1u == (gen + 1u) * nloc) {
;             __builtin_amdgcn_fence(__ATOMIC_RELEASE, "agent");
;             asm volatile("s_waitcnt vmcnt(0)" ::: "memory");
;             const unsigned og = xb_add(&bar[XB_TOP], 1u);
;             const unsigned tg = og / nx;
;             if (og + 1u == (tg + 1u) * nx) xb_add(&bar[XB_TOPGEN], 1u);
;             else XB_SPIN(xb_ld(&bar[XB_TOPGEN]) == tg, bar);
;             __builtin_amdgcn_fence(__ATOMIC_ACQUIRE, "agent");
;             xb_add(&bar[XB_XGEN(b.x)], 1u);
;             asm volatile("s_waitcnt vmcnt(0)" ::: "memory");
;         } else {
;             XB_SPIN(xb_ld(&bar[XB_XGEN(b.x)]) == gen, bar);
;             __builtin_amdgcn_fence(__ATOMIC_ACQUIRE, "agent");
;             asm volatile("s_waitcnt vmcnt(0)" ::: "memory");
;         }
;     }
;     __syncthreads();
; }
;     __device__ __forceinline__ bool next(int i, Unit& u) const {
;         if (i == 0) return base.next(0, u);
;         if (i > 1) return false;
;         const int tile = base.c >> 3, kz = base.c & 7;
.LBB0_1370:
	s_or_b64 exec, exec, s[6:7]
	v_readfirstlane_b32 s98, v212
	s_lshr_b32 s98, s98, 6
	s_cmp_eq_u32 s98, 0
	s_cbranch_scc1 .Lipf_skip_10
	s_getpc_b64 s[100:101]
	v_mbcnt_lo_u32_b32 v0, -1, 0
	v_mbcnt_hi_u32_b32 v0, -1, v0
	v_lshlrev_b32_e32 v0, 4, v0
	s_lshl_b32 s98, s98, 10
	v_add_u32_e32 v0, s98, v0
	global_load_dwordx4 v[2:5], v0, s[100:101]
	s_waitcnt vmcnt(0)
.Lipf_skip_10:
	s_add_u32 s6, s84, 0x14900000
	s_waitcnt lgkmcnt(0)
	s_barrier
	s_addc_u32 s7, s85, 0
	s_and_b64 vcc, exec, s[82:83]
	v_readfirstlane_b32 s16, v212
	s_cbranch_vccnz .LBB0_1390
	s_ashr_i32 s0, s2, 31
	s_lshr_b32 s0, s0, 29
	s_add_i32 s5, s2, s0
	s_and_b32 s0, s5, -8
	s_sub_i32 s4, s2, s0
	s_cmp_gt_i32 s4, -1
	s_cbranch_scc0 .LBB0_1373
	s_lshl_b32 s3, s4, 5
	s_ashr_i32 s5, s5, 3
	s_cbranch_execz .LBB0_1374
	s_branch .LBB0_1375
